# adds: k_mean rows staged into LDS only for the first of the four attention items of a (batch, head) slot
# baseline (speedup 1.0000x reference)
; __device__ __forceinline__ int opaque_tid() { int t = threadIdx.x; asm volatile("" : "+v"(t)); return t; }
; __device__ __forceinline__ float bflo(unsigned w) { return __uint_as_float(w << 16); }
; __device__ __forceinline__ float bfhi(unsigned w) { return __uint_as_float(w & 0xffff0000u); }
; #define ATT_LOAD(KR, VR, TI) do { const int t2_ = (TI), bi2_ = t2_ >> 2, kt2_ = t2_ & 3; const int blk2_ = (bi2_ == 0) ? j : bi2_ - 1; const size_t kr_ = rowb + blk2_ * 256 + kt2_ * 64; \
;         KR = *(const u32x4*)(z + (kr_ + skey) * 5120 + 1024 + h * 64 + schunk * 8); VR = *(const u32x4*)(z + (kr_ + vkey) * 5120 + 2048 + h * 64 + vchunk * 8); } while (0)
; #define kmean WSP(float, WS_KMEAN)
; __device__ __forceinline__ void attn_item(LAS unsigned char* lds, const bf16_t* z, const float* kmean, bf16_t* cat, int b, int h, int j) {
;     ...
;     const int tid = opaque_tid(), wave = __builtin_amdgcn_readfirstlane(tid >> 6), lane = tid & 63, lq = lane & 15, quad = lane >> 4;
;     const size_t rowb = (size_t)b * SEQ;
;     const int ntile = (j + 1) * 4;
;     const int skey = tid >> 3, schunk = tid & 7;
;     const int vkey = tid & 63, vchunk = tid >> 6;
;     u32x4 kreg, vreg, kreg2, vreg2;
;     ...
;     ATT_LOAD(kreg, vreg, 0);
;     ATT_LOAD(kreg2, vreg2, 1);
;     bf16x8 Qf[2][2]; int selm[2];
; #pragma unroll
;     for (int qg = 0; qg < 2; ++qg) { const int qi = wave * 32 + qg * 16 + lq; const bf16_t* qp = z + (rowb + j * 256 + qi) * 5120 + h * 64;
; #pragma unroll
;         for (int kh = 0; kh < 2; ++kh) Qf[qg][kh] = *(const bf16x8*)(qp + kh * 32 + quad * 8); }
;     if (tid < 256) {
;         const bf16_t* qp = z + (rowb + j * 256 + tid) * 5120 + h * 64;
;         float gate[7];
; #pragma unroll
;         for (int n = 0; n < 7; ++n) gate[n] = 0.f;
; #pragma unroll
;         for (int c = 0; c < 8; ++c) { const u32x4 w = *(const u32x4*)(qp + c * 8);
;             const float qf[8] = {bflo(w.x), bfhi(w.x), bflo(w.y), bfhi(w.y), bflo(w.z), bfhi(w.z), bflo(w.w), bfhi(w.w)};
; #pragma unroll
;             for (int n = 0; n < 7; ++n) if (n < j) { const float* km = kmean + (size_t)(((b * 16 + h) * 8) + n) * 64 + c * 8;
;                 const f32x4 k0 = *(const f32x4*)km, k1 = *(const f32x4*)(km + 4);
;                 gate[n] += qf[0] * k0[0] + qf[1] * k0[1] + qf[2] * k0[2] + qf[3] * k0[3] + qf[4] * k1[0] + qf[5] * k1[1] + qf[6] * k1[2] + qf[7] * k1[3]; } }
.LBB0_1497:
	s_mov_b64 s[2:3], s[0:1]
	v_mov_b32_e32 v44, v226
	s_lshl_b32 s8, s49, 8
	v_ashrrev_i32_e32 v102, 3, v44
	s_or_b32 s60, s58, s8
	s_mov_b32 s61, s59
	v_ashrrev_i32_e32 v103, 31, v102
	v_lshl_add_u64 v[0:1], s[60:61], 0, v[102:103]
	v_mov_b64_e32 v[2:3], s[64:65]
	v_mad_u64_u32 v[4:5], s[8:9], v0, s77, v[2:3]
	v_lshlrev_b32_e32 v0, 3, v44
	v_and_b32_e32 v0, 56, v0
	v_and_b32_e32 v117, 63, v44
	v_mad_i32_i24 v5, v1, s77, v5
	v_lshlrev_b32_e32 v8, 1, v0
	v_ashrrev_i32_e32 v7, 6, v44
	v_lshl_add_u64 v[0:1], v[4:5], 0, v[8:9]
	v_or_b32_e32 v6, s60, v117
	v_mov_b64_e32 v[4:5], s[92:93]
	v_mad_u64_u32 v[10:11], s[8:9], v6, s77, v[4:5]
	v_lshlrev_b32_e32 v104, 3, v7
	v_mad_i32_i24 v11, s59, v236, v11
	v_ashrrev_i32_e32 v105, 31, v104
	v_lshl_add_u64 v[10:11], v[10:11], 0, s[56:57]
	v_lshlrev_b64 v[42:43], 1, v[104:105]
	v_lshl_add_u64 v[10:11], v[10:11], 0, v[42:43]
	v_add_co_u32_e32 v10, vcc, s75, v10
	s_or_b32 s8, s60, 64
	s_mov_b32 s9, s59
	v_addc_co_u32_e32 v11, vcc, 0, v11, vcc
	global_load_dwordx4 v[38:41], v[0:1], off offset:2048
	global_load_dwordx4 v[34:37], v[10:11], off
	v_lshl_add_u64 v[0:1], s[8:9], 0, v[102:103]
	v_mad_u64_u32 v[2:3], s[10:11], v0, s77, v[2:3]
	v_mad_i32_i24 v3, v1, s77, v3
	v_lshl_add_u64 v[0:1], v[2:3], 0, v[8:9]
	v_or_b32_e32 v2, s8, v117
	v_mad_u64_u32 v[2:3], s[8:9], v2, s77, v[4:5]
	v_mad_i32_i24 v3, s59, v236, v3
	v_readfirstlane_b32 s38, v7
	v_lshl_add_u64 v[2:3], v[2:3], 0, s[56:57]
	v_and_b32_e32 v116, 15, v44
	v_lshl_add_u64 v[2:3], v[2:3], 0, v[42:43]
	s_lshl_b32 s81, s38, 5
	v_add_co_u32_e32 v2, vcc, s75, v2
	v_or_b32_e32 v98, s81, v116
	s_nop 0
	v_addc_co_u32_e32 v3, vcc, 0, v3, vcc
	global_load_dwordx4 v[30:33], v[0:1], off offset:2048
	global_load_dwordx4 v[26:29], v[2:3], off
	v_and_b32_e32 v0, 48, v44
	v_mov_b32_e32 v1, v9
	v_ashrrev_i32_e32 v99, 31, v98
	v_lshl_add_u64 v[0:1], s[64:65], 0, v[0:1]
	v_lshl_add_u64 v[2:3], s[60:61], 0, v[98:99]
	v_or_b32_e32 v100, 16, v98
	v_mad_u64_u32 v[4:5], s[8:9], v2, s77, v[0:1]
	v_ashrrev_i32_e32 v101, 31, v100
	v_mad_i32_i24 v5, v3, s77, v5
	v_lshl_add_u64 v[2:3], s[60:61], 0, v[100:101]
	v_mad_u64_u32 v[0:1], s[8:9], v2, s77, v[0:1]
	v_mad_i32_i24 v1, v3, s77, v1
	global_load_dwordx4 v[10:13], v[4:5], off
	global_load_dwordx4 v[14:17], v[4:5], off offset:64
	global_load_dwordx4 v[18:21], v[0:1], off
	global_load_dwordx4 v[22:25], v[0:1], off offset:64
	s_cmp_lg_u32 s85, 0
	s_cbranch_scc1 .Lmy_st_skip
	s_load_dwordx2 s[36:37], s[0:1], 0x110
	v_lshlrev_b32_e32 v154, 2, v226
	s_waitcnt lgkmcnt(0)
	s_add_u32 s36, s36, 0x19020000
	s_addc_u32 s37, s37, 0
	s_add_u32 s36, s36, s88
	s_addc_u32 s37, s37, s89
	s_nop 0
	global_load_dword v155, v154, s[36:37]
	v_mov_b32_e32 v203, s36
	v_sub_u32_e32 v203, 0xa000, v203
	v_add_u32_e32 v154, 0xa000, v154
	s_waitcnt vmcnt(0)
	ds_write_b32 v154, v155
	s_waitcnt lgkmcnt(0)
	s_barrier
.Lmy_st_skip:
	s_movk_i32 s8, 0x100
	v_cmp_gt_i32_e32 vcc, s8, v44
	s_and_saveexec_b64 s[22:23], vcc
	s_cbranch_execz .LBB0_1580
	v_ashrrev_i32_e32 v45, 31, v44
	v_lshl_add_u64 v[0:1], s[60:61], 0, v[44:45]
	v_mov_b64_e32 v[2:3], s[64:65]
	v_mad_u64_u32 v[46:47], s[8:9], v0, s77, v[2:3]
	v_mov_b32_e32 v0, v47
	v_mad_u64_u32 v[0:1], s[8:9], v1, s77, v[0:1]
	v_mov_b32_e32 v47, v0
	global_load_dwordx4 v[0:3], v[46:47], off
	global_load_dwordx4 v[158:161], v[46:47], off offset:16
	global_load_dwordx4 v[162:165], v[46:47], off offset:32
	global_load_dwordx4 v[166:169], v[46:47], off offset:48
	global_load_dwordx4 v[170:173], v[46:47], off offset:64
	global_load_dwordx4 v[174:177], v[46:47], off offset:80
	global_load_dwordx4 v[178:181], v[46:47], off offset:96
	global_load_dwordx4 v[182:185], v[46:47], off offset:112
	s_load_dwordx2 s[36:37], s[2:3], 0x110
	s_waitcnt lgkmcnt(0)
	s_add_u32 s2, s36, 0x19020000
	s_addc_u32 s3, s37, 0
	s_cmp_lg_u32 s49, 0
	s_cselect_b64 s[10:11], -1, 0
	s_cmp_eq_u32 s49, 0
	s_waitcnt vmcnt(0)
	v_lshlrev_b32_e32 v54, 16, v0
	v_and_b32_e32 v55, 0xffff0000, v0
	v_and_b32_e32 v51, 0xffff0000, v1
	v_lshlrev_b32_e32 v50, 16, v1
	v_and_b32_e32 v53, 0xffff0000, v2
	v_lshlrev_b32_e32 v52, 16, v2
	v_and_b32_e32 v49, 0xffff0000, v3
	v_lshlrev_b32_e32 v48, 16, v3
	s_cbranch_scc1 .LBB0_1500
	s_add_u32 s8, s2, s88
	s_addc_u32 s9, s3, s89
	v_add_u32_e32 v157, s8, v203
	ds_read_b128 v[0:3], v157 offset:16
	ds_read_b128 v[56:59], v157
	s_waitcnt lgkmcnt(1)
	v_pk_mul_f32 v[0:1], v[0:1], v[52:53]
	s_waitcnt lgkmcnt(0)
	v_pk_mul_f32 v[4:5], v[56:57], v[54:55]
	v_pk_mul_f32 v[56:57], v[58:59], v[50:51]
	v_add_f32_e32 v4, v4, v5
	v_add_f32_e32 v4, v56, v4
	v_add_f32_e32 v4, v57, v4
	v_add_f32_e32 v0, v0, v4
	v_pk_mul_f32 v[2:3], v[2:3], v[48:49]
	v_add_f32_e32 v0, v1, v0
	v_add_f32_e32 v0, v2, v0
	v_add_f32_e32 v0, v3, v0
	v_add_f32_e32 v0, 0, v0
	s_branch .LBB0_1501

; __device__ __forceinline__ float bflo(unsigned w) { return __uint_as_float(w << 16); }
; __device__ __forceinline__ float bfhi(unsigned w) { return __uint_as_float(w & 0xffff0000u); }
; #define kmean WSP(float, WS_KMEAN)
; __device__ __forceinline__ void attn_item(LAS unsigned char* lds, const bf16_t* z, const float* kmean, bf16_t* cat, int b, int h, int j) {
;     ...
; #pragma unroll
;         for (int c = 0; c < 8; ++c) { const u32x4 w = *(const u32x4*)(qp + c * 8);
;             const float qf[8] = {bflo(w.x), bfhi(w.x), bflo(w.y), bfhi(w.y), bflo(w.z), bfhi(w.z), bflo(w.w), bfhi(w.w)};
; #pragma unroll
;             for (int n = 0; n < 7; ++n) if (n < j) { const float* km = kmean + (size_t)(((b * 16 + h) * 8) + n) * 64 + c * 8;
;                 const f32x4 k0 = *(const f32x4*)km, k1 = *(const f32x4*)(km + 4);
;                 gate[n] += qf[0] * k0[0] + qf[1] * k0[1] + qf[2] * k0[2] + qf[3] * k0[3] + qf[4] * k1[0] + qf[5] * k1[1] + qf[6] * k1[2] + qf[7] * k1[3]; } }
.LBB0_1507:
	s_add_u32 s2, s2, s6
	s_addc_u32 s3, s3, s7
	v_add_u32_e32 v157, s2, v203
	ds_read_b128 v[56:59], v157
	ds_read_b128 v[60:63], v157 offset:16
	s_waitcnt lgkmcnt(1)
	v_pk_mul_f32 v[54:55], v[56:57], v[54:55]
	v_pk_mul_f32 v[50:51], v[58:59], v[50:51]
	v_add_f32_e32 v45, v54, v55
	v_add_f32_e32 v45, v50, v45
	s_waitcnt lgkmcnt(0)
	v_pk_mul_f32 v[52:53], v[60:61], v[52:53]
	v_add_f32_e32 v45, v51, v45
	v_add_f32_e32 v45, v52, v45
	v_pk_mul_f32 v[48:49], v[62:63], v[48:49]
	v_add_f32_e32 v45, v53, v45
	v_add_f32_e32 v45, v48, v45
	v_add_f32_e32 v45, v49, v45
	v_add_f32_e32 v6, v6, v45
.LBB0_1508:
	v_mov_b64_e32 v[56:57], v[158:159]
	v_mov_b64_e32 v[58:59], v[160:161]
	s_add_u32 s2, s36, 0x19020020
	v_cndmask_b32_e64 v45, 0, 1, s[10:11]
	s_addc_u32 s3, s37, 0
	v_cmp_ne_u32_e64 s[8:9], 1, v45
	s_andn2_b64 vcc, exec, s[10:11]
	s_waitcnt vmcnt(0)
	v_lshlrev_b32_e32 v54, 16, v56
	v_and_b32_e32 v55, 0xffff0000, v56
	v_and_b32_e32 v51, 0xffff0000, v57
	v_lshlrev_b32_e32 v50, 16, v57
	v_and_b32_e32 v53, 0xffff0000, v58
	v_lshlrev_b32_e32 v52, 16, v58
	v_and_b32_e32 v49, 0xffff0000, v59
	v_lshlrev_b32_e32 v48, 16, v59
	s_cbranch_vccnz .LBB0_1510
	s_add_u32 s10, s2, s88
	s_addc_u32 s11, s3, s89
	v_add_u32_e32 v157, s10, v203
	ds_read_b128 v[56:59], v157
	ds_read_b128 v[60:63], v157 offset:16
	s_waitcnt lgkmcnt(1)
	v_pk_mul_f32 v[56:57], v[56:57], v[54:55]
	v_pk_mul_f32 v[58:59], v[58:59], v[50:51]
	v_add_f32_e32 v45, v56, v57
	v_add_f32_e32 v45, v58, v45
	s_waitcnt lgkmcnt(0)
	v_pk_mul_f32 v[60:61], v[60:61], v[52:53]
	v_add_f32_e32 v45, v59, v45
	v_add_f32_e32 v45, v60, v45
	v_pk_mul_f32 v[62:63], v[62:63], v[48:49]
	v_add_f32_e32 v45, v61, v45
	v_add_f32_e32 v45, v62, v45
	v_add_f32_e32 v45, v63, v45
	v_add_f32_e32 v0, v0, v45

; __device__ __forceinline__ float bflo(unsigned w) { return __uint_as_float(w << 16); }
; __device__ __forceinline__ float bfhi(unsigned w) { return __uint_as_float(w & 0xffff0000u); }
; #define kmean WSP(float, WS_KMEAN)
; __device__ __forceinline__ void attn_item(LAS unsigned char* lds, const bf16_t* z, const float* kmean, bf16_t* cat, int b, int h, int j) {
;     ...
; #pragma unroll
;         for (int c = 0; c < 8; ++c) { const u32x4 w = *(const u32x4*)(qp + c * 8);
;             const float qf[8] = {bflo(w.x), bfhi(w.x), bflo(w.y), bfhi(w.y), bflo(w.z), bfhi(w.z), bflo(w.w), bfhi(w.w)};
; #pragma unroll
;             for (int n = 0; n < 7; ++n) if (n < j) { const float* km = kmean + (size_t)(((b * 16 + h) * 8) + n) * 64 + c * 8;
;                 const f32x4 k0 = *(const f32x4*)km, k1 = *(const f32x4*)(km + 4);
;                 gate[n] += qf[0] * k0[0] + qf[1] * k0[1] + qf[2] * k0[2] + qf[3] * k0[3] + qf[4] * k1[0] + qf[5] * k1[1] + qf[6] * k1[2] + qf[7] * k1[3]; } }
.LBB0_1517:
	v_mov_b64_e32 v[56:57], v[162:163]
	v_mov_b64_e32 v[58:59], v[164:165]
	s_add_u32 s2, s36, 0x19020040
	s_addc_u32 s3, s37, 0
	s_and_b64 vcc, exec, s[8:9]
	s_waitcnt vmcnt(0)
	v_lshlrev_b32_e32 v54, 16, v56
	v_and_b32_e32 v55, 0xffff0000, v56
	v_and_b32_e32 v51, 0xffff0000, v57
	v_lshlrev_b32_e32 v50, 16, v57
	v_and_b32_e32 v53, 0xffff0000, v58
	v_lshlrev_b32_e32 v52, 16, v58
	v_and_b32_e32 v49, 0xffff0000, v59
	v_lshlrev_b32_e32 v48, 16, v59
	s_cbranch_vccnz .LBB0_1519
	s_add_u32 s40, s2, s88
	s_addc_u32 s41, s3, s89
	v_add_u32_e32 v157, s40, v203
	ds_read_b128 v[56:59], v157
	ds_read_b128 v[60:63], v157 offset:16
	s_waitcnt lgkmcnt(1)
	v_pk_mul_f32 v[56:57], v[56:57], v[54:55]
	v_pk_mul_f32 v[58:59], v[58:59], v[50:51]
	v_add_f32_e32 v45, v56, v57
	v_add_f32_e32 v45, v58, v45
	s_waitcnt lgkmcnt(0)
	v_pk_mul_f32 v[60:61], v[60:61], v[52:53]
	v_add_f32_e32 v45, v59, v45
	v_add_f32_e32 v45, v60, v45
	v_pk_mul_f32 v[62:63], v[62:63], v[48:49]
	v_add_f32_e32 v45, v61, v45
	v_add_f32_e32 v45, v62, v45
	v_add_f32_e32 v45, v63, v45
	v_add_f32_e32 v0, v0, v45

; __device__ __forceinline__ float bflo(unsigned w) { return __uint_as_float(w << 16); }
; __device__ __forceinline__ float bfhi(unsigned w) { return __uint_as_float(w & 0xffff0000u); }
; #define kmean WSP(float, WS_KMEAN)
; __device__ __forceinline__ void attn_item(LAS unsigned char* lds, const bf16_t* z, const float* kmean, bf16_t* cat, int b, int h, int j) {
;     ...
; #pragma unroll
;         for (int c = 0; c < 8; ++c) { const u32x4 w = *(const u32x4*)(qp + c * 8);
;             const float qf[8] = {bflo(w.x), bfhi(w.x), bflo(w.y), bfhi(w.y), bflo(w.z), bfhi(w.z), bflo(w.w), bfhi(w.w)};
; #pragma unroll
;             for (int n = 0; n < 7; ++n) if (n < j) { const float* km = kmean + (size_t)(((b * 16 + h) * 8) + n) * 64 + c * 8;
;                 const f32x4 k0 = *(const f32x4*)km, k1 = *(const f32x4*)(km + 4);
;                 gate[n] += qf[0] * k0[0] + qf[1] * k0[1] + qf[2] * k0[2] + qf[3] * k0[3] + qf[4] * k1[0] + qf[5] * k1[1] + qf[6] * k1[2] + qf[7] * k1[3]; } }
.LBB0_1526:
	v_mov_b64_e32 v[56:57], v[166:167]
	v_mov_b64_e32 v[58:59], v[168:169]
	s_add_u32 s2, s36, 0x19020060
	s_addc_u32 s3, s37, 0
	s_and_b64 vcc, exec, s[8:9]
	s_waitcnt vmcnt(0)
	v_lshlrev_b32_e32 v54, 16, v56
	v_and_b32_e32 v55, 0xffff0000, v56
	v_and_b32_e32 v51, 0xffff0000, v57
	v_lshlrev_b32_e32 v50, 16, v57
	v_and_b32_e32 v53, 0xffff0000, v58
	v_lshlrev_b32_e32 v52, 16, v58
	v_and_b32_e32 v49, 0xffff0000, v59
	v_lshlrev_b32_e32 v48, 16, v59
	s_cbranch_vccnz .LBB0_1528
	s_add_u32 s40, s2, s88
	s_addc_u32 s41, s3, s89
	v_add_u32_e32 v157, s40, v203
	ds_read_b128 v[56:59], v157
	ds_read_b128 v[60:63], v157 offset:16
	s_waitcnt lgkmcnt(1)
	v_pk_mul_f32 v[56:57], v[56:57], v[54:55]
	v_pk_mul_f32 v[58:59], v[58:59], v[50:51]
	v_add_f32_e32 v45, v56, v57
	v_add_f32_e32 v45, v58, v45
	s_waitcnt lgkmcnt(0)
	v_pk_mul_f32 v[60:61], v[60:61], v[52:53]
	v_add_f32_e32 v45, v59, v45
	v_add_f32_e32 v45, v60, v45
	v_pk_mul_f32 v[62:63], v[62:63], v[48:49]
	v_add_f32_e32 v45, v61, v45
	v_add_f32_e32 v45, v62, v45
	v_add_f32_e32 v45, v63, v45
	v_add_f32_e32 v0, v0, v45

; __device__ __forceinline__ float bflo(unsigned w) { return __uint_as_float(w << 16); }
; __device__ __forceinline__ float bfhi(unsigned w) { return __uint_as_float(w & 0xffff0000u); }
; #define kmean WSP(float, WS_KMEAN)
; __device__ __forceinline__ void attn_item(LAS unsigned char* lds, const bf16_t* z, const float* kmean, bf16_t* cat, int b, int h, int j) {
;     ...
; #pragma unroll
;         for (int c = 0; c < 8; ++c) { const u32x4 w = *(const u32x4*)(qp + c * 8);
;             const float qf[8] = {bflo(w.x), bfhi(w.x), bflo(w.y), bfhi(w.y), bflo(w.z), bfhi(w.z), bflo(w.w), bfhi(w.w)};
; #pragma unroll
;             for (int n = 0; n < 7; ++n) if (n < j) { const float* km = kmean + (size_t)(((b * 16 + h) * 8) + n) * 64 + c * 8;
;                 const f32x4 k0 = *(const f32x4*)km, k1 = *(const f32x4*)(km + 4);
;                 gate[n] += qf[0] * k0[0] + qf[1] * k0[1] + qf[2] * k0[2] + qf[3] * k0[3] + qf[4] * k1[0] + qf[5] * k1[1] + qf[6] * k1[2] + qf[7] * k1[3]; } }
.LBB0_1535:
	v_mov_b64_e32 v[56:57], v[170:171]
	v_mov_b64_e32 v[58:59], v[172:173]
	s_add_u32 s2, s36, 0x19020080
	s_addc_u32 s3, s37, 0
	s_and_b64 vcc, exec, s[8:9]
	s_waitcnt vmcnt(0)
	v_lshlrev_b32_e32 v54, 16, v56
	v_and_b32_e32 v55, 0xffff0000, v56
	v_and_b32_e32 v51, 0xffff0000, v57
	v_lshlrev_b32_e32 v50, 16, v57
	v_and_b32_e32 v53, 0xffff0000, v58
	v_lshlrev_b32_e32 v52, 16, v58
	v_and_b32_e32 v49, 0xffff0000, v59
	v_lshlrev_b32_e32 v48, 16, v59
	s_cbranch_vccnz .LBB0_1537
	s_add_u32 s40, s2, s88
	s_addc_u32 s41, s3, s89
	v_add_u32_e32 v157, s40, v203
	ds_read_b128 v[56:59], v157
	ds_read_b128 v[60:63], v157 offset:16
	s_waitcnt lgkmcnt(1)
	v_pk_mul_f32 v[56:57], v[56:57], v[54:55]
	v_pk_mul_f32 v[58:59], v[58:59], v[50:51]
	v_add_f32_e32 v45, v56, v57
	v_add_f32_e32 v45, v58, v45
	s_waitcnt lgkmcnt(0)
	v_pk_mul_f32 v[60:61], v[60:61], v[52:53]
	v_add_f32_e32 v45, v59, v45
	v_add_f32_e32 v45, v60, v45
	v_pk_mul_f32 v[62:63], v[62:63], v[48:49]
	v_add_f32_e32 v45, v61, v45
	v_add_f32_e32 v45, v62, v45
	v_add_f32_e32 v45, v63, v45
	v_add_f32_e32 v0, v0, v45

; __device__ __forceinline__ float bflo(unsigned w) { return __uint_as_float(w << 16); }
; __device__ __forceinline__ float bfhi(unsigned w) { return __uint_as_float(w & 0xffff0000u); }
; #define kmean WSP(float, WS_KMEAN)
; __device__ __forceinline__ void attn_item(LAS unsigned char* lds, const bf16_t* z, const float* kmean, bf16_t* cat, int b, int h, int j) {
;     ...
; #pragma unroll
;         for (int c = 0; c < 8; ++c) { const u32x4 w = *(const u32x4*)(qp + c * 8);
;             const float qf[8] = {bflo(w.x), bfhi(w.x), bflo(w.y), bfhi(w.y), bflo(w.z), bfhi(w.z), bflo(w.w), bfhi(w.w)};
; #pragma unroll
;             for (int n = 0; n < 7; ++n) if (n < j) { const float* km = kmean + (size_t)(((b * 16 + h) * 8) + n) * 64 + c * 8;
;                 const f32x4 k0 = *(const f32x4*)km, k1 = *(const f32x4*)(km + 4);
;                 gate[n] += qf[0] * k0[0] + qf[1] * k0[1] + qf[2] * k0[2] + qf[3] * k0[3] + qf[4] * k1[0] + qf[5] * k1[1] + qf[6] * k1[2] + qf[7] * k1[3]; } }
.LBB0_1544:
	v_mov_b64_e32 v[56:57], v[174:175]
	v_mov_b64_e32 v[58:59], v[176:177]
	s_add_u32 s2, s36, 0x190200a0
	s_addc_u32 s3, s37, 0
	s_and_b64 vcc, exec, s[8:9]
	s_waitcnt vmcnt(0)
	v_lshlrev_b32_e32 v54, 16, v56
	v_and_b32_e32 v55, 0xffff0000, v56
	v_and_b32_e32 v51, 0xffff0000, v57
	v_lshlrev_b32_e32 v50, 16, v57
	v_and_b32_e32 v53, 0xffff0000, v58
	v_lshlrev_b32_e32 v52, 16, v58
	v_and_b32_e32 v49, 0xffff0000, v59
	v_lshlrev_b32_e32 v48, 16, v59
	s_cbranch_vccnz .LBB0_1546
	s_add_u32 s40, s2, s88
	s_addc_u32 s41, s3, s89
	v_add_u32_e32 v157, s40, v203
	ds_read_b128 v[56:59], v157
	ds_read_b128 v[60:63], v157 offset:16
	s_waitcnt lgkmcnt(1)
	v_pk_mul_f32 v[56:57], v[56:57], v[54:55]
	v_pk_mul_f32 v[58:59], v[58:59], v[50:51]
	v_add_f32_e32 v45, v56, v57
	v_add_f32_e32 v45, v58, v45
	s_waitcnt lgkmcnt(0)
	v_pk_mul_f32 v[60:61], v[60:61], v[52:53]
	v_add_f32_e32 v45, v59, v45
	v_add_f32_e32 v45, v60, v45
	v_pk_mul_f32 v[62:63], v[62:63], v[48:49]
	v_add_f32_e32 v45, v61, v45
	v_add_f32_e32 v45, v62, v45
	v_add_f32_e32 v45, v63, v45
	v_add_f32_e32 v0, v0, v45

; __device__ __forceinline__ float bflo(unsigned w) { return __uint_as_float(w << 16); }
; __device__ __forceinline__ float bfhi(unsigned w) { return __uint_as_float(w & 0xffff0000u); }
; #define kmean WSP(float, WS_KMEAN)
; __device__ __forceinline__ void attn_item(LAS unsigned char* lds, const bf16_t* z, const float* kmean, bf16_t* cat, int b, int h, int j) {
;     ...
; #pragma unroll
;         for (int c = 0; c < 8; ++c) { const u32x4 w = *(const u32x4*)(qp + c * 8);
;             const float qf[8] = {bflo(w.x), bfhi(w.x), bflo(w.y), bfhi(w.y), bflo(w.z), bfhi(w.z), bflo(w.w), bfhi(w.w)};
; #pragma unroll
;             for (int n = 0; n < 7; ++n) if (n < j) { const float* km = kmean + (size_t)(((b * 16 + h) * 8) + n) * 64 + c * 8;
;                 const f32x4 k0 = *(const f32x4*)km, k1 = *(const f32x4*)(km + 4);
;                 gate[n] += qf[0] * k0[0] + qf[1] * k0[1] + qf[2] * k0[2] + qf[3] * k0[3] + qf[4] * k1[0] + qf[5] * k1[1] + qf[6] * k1[2] + qf[7] * k1[3]; } }
.LBB0_1553:
	v_mov_b64_e32 v[56:57], v[178:179]
	v_mov_b64_e32 v[58:59], v[180:181]
	s_add_u32 s2, s36, 0x190200c0
	s_addc_u32 s3, s37, 0
	s_and_b64 vcc, exec, s[8:9]
	s_waitcnt vmcnt(0)
	v_lshlrev_b32_e32 v54, 16, v56
	v_and_b32_e32 v55, 0xffff0000, v56
	v_and_b32_e32 v51, 0xffff0000, v57
	v_lshlrev_b32_e32 v50, 16, v57
	v_and_b32_e32 v53, 0xffff0000, v58
	v_lshlrev_b32_e32 v52, 16, v58
	v_and_b32_e32 v49, 0xffff0000, v59
	v_lshlrev_b32_e32 v48, 16, v59
	s_cbranch_vccnz .LBB0_1555
	s_add_u32 s40, s2, s88
	s_addc_u32 s41, s3, s89
	v_add_u32_e32 v157, s40, v203
	ds_read_b128 v[56:59], v157
	ds_read_b128 v[60:63], v157 offset:16
	s_waitcnt lgkmcnt(1)
	v_pk_mul_f32 v[56:57], v[56:57], v[54:55]
	v_pk_mul_f32 v[58:59], v[58:59], v[50:51]
	v_add_f32_e32 v45, v56, v57
	v_add_f32_e32 v45, v58, v45
	s_waitcnt lgkmcnt(0)
	v_pk_mul_f32 v[60:61], v[60:61], v[52:53]
	v_add_f32_e32 v45, v59, v45
	v_add_f32_e32 v45, v60, v45
	v_pk_mul_f32 v[62:63], v[62:63], v[48:49]
	v_add_f32_e32 v45, v61, v45
	v_add_f32_e32 v45, v62, v45
	v_add_f32_e32 v45, v63, v45
	v_add_f32_e32 v0, v0, v45

; __device__ __forceinline__ float bflo(unsigned w) { return __uint_as_float(w << 16); }
; __device__ __forceinline__ float bfhi(unsigned w) { return __uint_as_float(w & 0xffff0000u); }
; #define kmean WSP(float, WS_KMEAN)
; __device__ __forceinline__ void attn_item(LAS unsigned char* lds, const bf16_t* z, const float* kmean, bf16_t* cat, int b, int h, int j) {
;     ...
; #pragma unroll
;         for (int c = 0; c < 8; ++c) { const u32x4 w = *(const u32x4*)(qp + c * 8);
;             const float qf[8] = {bflo(w.x), bfhi(w.x), bflo(w.y), bfhi(w.y), bflo(w.z), bfhi(w.z), bflo(w.w), bfhi(w.w)};
; #pragma unroll
;             for (int n = 0; n < 7; ++n) if (n < j) { const float* km = kmean + (size_t)(((b * 16 + h) * 8) + n) * 64 + c * 8;
;                 const f32x4 k0 = *(const f32x4*)km, k1 = *(const f32x4*)(km + 4);
;                 gate[n] += qf[0] * k0[0] + qf[1] * k0[1] + qf[2] * k0[2] + qf[3] * k0[3] + qf[4] * k1[0] + qf[5] * k1[1] + qf[6] * k1[2] + qf[7] * k1[3]; } }
.LBB0_1562:
	v_mov_b64_e32 v[54:55], v[182:183]
	v_mov_b64_e32 v[56:57], v[184:185]
	s_add_u32 s2, s36, 0x190200e0
	s_addc_u32 s3, s37, 0
	s_and_b64 vcc, exec, s[8:9]
	s_waitcnt vmcnt(0)
	v_lshlrev_b32_e32 v52, 16, v54
	v_and_b32_e32 v53, 0xffff0000, v54
	v_and_b32_e32 v49, 0xffff0000, v55
	v_lshlrev_b32_e32 v48, 16, v55
	v_and_b32_e32 v51, 0xffff0000, v56
	v_lshlrev_b32_e32 v50, 16, v56
	v_and_b32_e32 v47, 0xffff0000, v57
	v_lshlrev_b32_e32 v46, 16, v57
	s_cbranch_vccnz .LBB0_1564
	s_add_u32 s36, s2, s88
	s_addc_u32 s37, s3, s89
	v_add_u32_e32 v157, s36, v203
	ds_read_b128 v[54:57], v157
	ds_read_b128 v[58:61], v157 offset:16
	s_waitcnt lgkmcnt(1)
	v_pk_mul_f32 v[54:55], v[54:55], v[52:53]
	v_pk_mul_f32 v[56:57], v[56:57], v[48:49]
	v_add_f32_e32 v45, v54, v55
	v_add_f32_e32 v45, v56, v45
	s_waitcnt lgkmcnt(0)
	v_pk_mul_f32 v[58:59], v[58:59], v[50:51]
	v_add_f32_e32 v45, v57, v45
	v_add_f32_e32 v45, v58, v45
	v_pk_mul_f32 v[60:61], v[60:61], v[46:47]
	v_add_f32_e32 v45, v59, v45
	v_add_f32_e32 v45, v60, v45
	v_add_f32_e32 v45, v61, v45
	v_add_f32_e32 v0, v0, v45

; __device__ __forceinline__ float bflo(unsigned w) { return __uint_as_float(w << 16); }
; __device__ __forceinline__ float bfhi(unsigned w) { return __uint_as_float(w & 0xffff0000u); }
; #define kmean WSP(float, WS_KMEAN)
; __device__ __forceinline__ void attn_item(LAS unsigned char* lds, const bf16_t* z, const float* kmean, bf16_t* cat, int b, int h, int j) {
;     ...
; #pragma unroll
;         for (int c = 0; c < 8; ++c) { const u32x4 w = *(const u32x4*)(qp + c * 8);
;             const float qf[8] = {bflo(w.x), bfhi(w.x), bflo(w.y), bfhi(w.y), bflo(w.z), bfhi(w.z), bflo(w.w), bfhi(w.w)};
; #pragma unroll
;             for (int n = 0; n < 7; ++n) if (n < j) { const float* km = kmean + (size_t)(((b * 16 + h) * 8) + n) * 64 + c * 8;
;                 const f32x4 k0 = *(const f32x4*)km, k1 = *(const f32x4*)(km + 4);
;                 gate[n] += qf[0] * k0[0] + qf[1] * k0[1] + qf[2] * k0[2] + qf[3] * k0[3] + qf[4] * k1[0] + qf[5] * k1[1] + qf[6] * k1[2] + qf[7] * k1[3]; } }
.LBB0_1621:
	s_add_u32 s8, s2, s4
	s_addc_u32 s9, s3, s5
	v_add_u32_e32 v157, s8, v203
	ds_read_b128 v[56:59], v157
	ds_read_b128 v[60:63], v157 offset:16
	s_waitcnt lgkmcnt(1)
	v_pk_mul_f32 v[56:57], v[56:57], v[54:55]
	v_pk_mul_f32 v[58:59], v[58:59], v[50:51]
	v_add_f32_e32 v45, v56, v57
	v_add_f32_e32 v45, v58, v45
	s_waitcnt lgkmcnt(0)
	v_pk_mul_f32 v[60:61], v[60:61], v[52:53]
	v_add_f32_e32 v45, v59, v45
	v_add_f32_e32 v45, v60, v45
	v_pk_mul_f32 v[62:63], v[62:63], v[48:49]
	v_add_f32_e32 v45, v61, v45
	v_add_f32_e32 v45, v62, v45
	v_add_f32_e32 v45, v63, v45
	v_add_f32_e32 v1, v1, v45
	s_cmp_gt_u32 s49, 2
	s_cselect_b64 s[34:35], -1, 0
	s_cmp_lt_u32 s49, 3
	s_cbranch_scc1 .LBB0_1503
.LBB0_1622:
	s_add_u32 s8, s2, s52
	s_addc_u32 s9, s3, s53
	v_add_u32_e32 v157, s8, v203
	ds_read_b128 v[56:59], v157
	ds_read_b128 v[60:63], v157 offset:16
	s_waitcnt lgkmcnt(1)
	v_pk_mul_f32 v[56:57], v[56:57], v[54:55]
	v_pk_mul_f32 v[58:59], v[58:59], v[50:51]
	v_add_f32_e32 v45, v56, v57
	v_add_f32_e32 v45, v58, v45
	s_waitcnt lgkmcnt(0)
	v_pk_mul_f32 v[60:61], v[60:61], v[52:53]
	v_add_f32_e32 v45, v59, v45
	v_add_f32_e32 v45, v60, v45
	v_pk_mul_f32 v[62:63], v[62:63], v[48:49]
	v_add_f32_e32 v45, v61, v45
	v_add_f32_e32 v45, v62, v45
	v_add_f32_e32 v45, v63, v45
	v_add_f32_e32 v2, v2, v45
	s_cmp_gt_u32 s49, 3
	s_cselect_b64 s[30:31], -1, 0
	s_cmp_lt_u32 s49, 4
	s_cbranch_scc1 .LBB0_1504
.LBB0_1623:
	s_add_u32 s8, s2, s54
	s_addc_u32 s9, s3, s55
	v_add_u32_e32 v157, s8, v203
	ds_read_b128 v[56:59], v157
	ds_read_b128 v[60:63], v157 offset:16
	s_waitcnt lgkmcnt(1)
	v_pk_mul_f32 v[56:57], v[56:57], v[54:55]
	v_pk_mul_f32 v[58:59], v[58:59], v[50:51]
	v_add_f32_e32 v45, v56, v57
	v_add_f32_e32 v45, v58, v45
	s_waitcnt lgkmcnt(0)
	v_pk_mul_f32 v[60:61], v[60:61], v[52:53]
	v_add_f32_e32 v45, v59, v45
	v_add_f32_e32 v45, v60, v45
	v_pk_mul_f32 v[62:63], v[62:63], v[48:49]
	v_add_f32_e32 v45, v61, v45
	v_add_f32_e32 v45, v62, v45
	v_add_f32_e32 v45, v63, v45
	v_add_f32_e32 v3, v3, v45
	s_cmp_gt_u32 s49, 4
	s_cselect_b64 s[26:27], -1, 0
	s_cmp_lt_u32 s49, 5
	s_cbranch_scc1 .LBB0_1505
.LBB0_1624:
	s_add_u32 s8, s2, s46
	s_addc_u32 s9, s3, s47
	v_add_u32_e32 v157, s8, v203
	ds_read_b128 v[56:59], v157
	ds_read_b128 v[60:63], v157 offset:16
	s_waitcnt lgkmcnt(1)
	v_pk_mul_f32 v[56:57], v[56:57], v[54:55]
	v_pk_mul_f32 v[58:59], v[58:59], v[50:51]
	v_add_f32_e32 v45, v56, v57
	v_add_f32_e32 v45, v58, v45
	s_waitcnt lgkmcnt(0)
	v_pk_mul_f32 v[60:61], v[60:61], v[52:53]
	v_add_f32_e32 v45, v59, v45
	v_add_f32_e32 v45, v60, v45
	v_pk_mul_f32 v[62:63], v[62:63], v[48:49]
	v_add_f32_e32 v45, v61, v45
	v_add_f32_e32 v45, v62, v45
	v_add_f32_e32 v45, v63, v45
	v_add_f32_e32 v4, v4, v45
	s_cmp_gt_u32 s49, 5
	s_cselect_b64 s[24:25], -1, 0
	s_cmp_lt_u32 s49, 6
	s_cbranch_scc1 .LBB0_1506
.LBB0_1625:
	s_add_u32 s8, s2, s90
	s_addc_u32 s9, s3, s91
	v_add_u32_e32 v157, s8, v203
	ds_read_b128 v[56:59], v157
	ds_read_b128 v[60:63], v157 offset:16
	s_waitcnt lgkmcnt(1)
	v_pk_mul_f32 v[56:57], v[56:57], v[54:55]
	v_pk_mul_f32 v[58:59], v[58:59], v[50:51]
	v_add_f32_e32 v45, v56, v57
	v_add_f32_e32 v45, v58, v45
	s_waitcnt lgkmcnt(0)
	v_pk_mul_f32 v[60:61], v[60:61], v[52:53]
	v_add_f32_e32 v45, v59, v45
	v_add_f32_e32 v45, v60, v45
	v_pk_mul_f32 v[62:63], v[62:63], v[48:49]
	v_add_f32_e32 v45, v61, v45
	v_add_f32_e32 v45, v62, v45
	v_add_f32_e32 v45, v63, v45
	v_add_f32_e32 v5, v5, v45
	s_cmp_eq_u32 s49, 7
	s_cselect_b64 s[28:29], -1, 0
	s_cmp_lg_u32 s49, 7
	s_cbranch_scc0 .LBB0_1507
	s_branch .LBB0_1508
.LBB0_1626:
	s_add_u32 s10, s2, s4
	s_addc_u32 s11, s3, s5
	v_add_u32_e32 v157, s10, v203
	ds_read_b128 v[56:59], v157
	ds_read_b128 v[60:63], v157 offset:16
	s_waitcnt lgkmcnt(1)
	v_pk_mul_f32 v[56:57], v[56:57], v[54:55]
	v_pk_mul_f32 v[58:59], v[58:59], v[50:51]
	v_add_f32_e32 v45, v56, v57
	v_add_f32_e32 v45, v58, v45
	s_waitcnt lgkmcnt(0)
	v_pk_mul_f32 v[60:61], v[60:61], v[52:53]
	v_add_f32_e32 v45, v59, v45
	v_add_f32_e32 v45, v60, v45
	v_pk_mul_f32 v[62:63], v[62:63], v[48:49]
	v_add_f32_e32 v45, v61, v45
	v_add_f32_e32 v45, v62, v45
	v_add_f32_e32 v45, v63, v45
	v_add_f32_e32 v1, v1, v45
	v_cndmask_b32_e64 v45, 0, 1, s[34:35]
	v_cmp_ne_u32_e64 s[18:19], 1, v45
	s_andn2_b64 vcc, exec, s[34:35]
	s_cbranch_vccnz .LBB0_1512
.LBB0_1627:
	s_add_u32 s10, s2, s52
	s_addc_u32 s11, s3, s53
	v_add_u32_e32 v157, s10, v203
	ds_read_b128 v[56:59], v157
	ds_read_b128 v[60:63], v157 offset:16
	s_waitcnt lgkmcnt(1)
	v_pk_mul_f32 v[56:57], v[56:57], v[54:55]
	v_pk_mul_f32 v[58:59], v[58:59], v[50:51]
	v_add_f32_e32 v45, v56, v57
	v_add_f32_e32 v45, v58, v45
	s_waitcnt lgkmcnt(0)
	v_pk_mul_f32 v[60:61], v[60:61], v[52:53]
	v_add_f32_e32 v45, v59, v45
	v_add_f32_e32 v45, v60, v45
	v_pk_mul_f32 v[62:63], v[62:63], v[48:49]
	v_add_f32_e32 v45, v61, v45
	v_add_f32_e32 v45, v62, v45
	v_add_f32_e32 v45, v63, v45
	v_add_f32_e32 v2, v2, v45
	v_cndmask_b32_e64 v45, 0, 1, s[30:31]
	v_cmp_ne_u32_e64 s[10:11], 1, v45
	s_andn2_b64 vcc, exec, s[30:31]
	s_cbranch_vccnz .LBB0_1513
; __device__ __forceinline__ float bflo(unsigned w) { return __uint_as_float(w << 16); }
; __device__ __forceinline__ float bfhi(unsigned w) { return __uint_as_float(w & 0xffff0000u); }
; #define kmean WSP(float, WS_KMEAN)
; __device__ __forceinline__ void attn_item(LAS unsigned char* lds, const bf16_t* z, const float* kmean, bf16_t* cat, int b, int h, int j) {
;     ...
; #pragma unroll
;         for (int c = 0; c < 8; ++c) { const u32x4 w = *(const u32x4*)(qp + c * 8);
;             const float qf[8] = {bflo(w.x), bfhi(w.x), bflo(w.y), bfhi(w.y), bflo(w.z), bfhi(w.z), bflo(w.w), bfhi(w.w)};
; #pragma unroll
;             for (int n = 0; n < 7; ++n) if (n < j) { const float* km = kmean + (size_t)(((b * 16 + h) * 8) + n) * 64 + c * 8;
;                 const f32x4 k0 = *(const f32x4*)km, k1 = *(const f32x4*)(km + 4);
;                 gate[n] += qf[0] * k0[0] + qf[1] * k0[1] + qf[2] * k0[2] + qf[3] * k0[3] + qf[4] * k1[0] + qf[5] * k1[1] + qf[6] * k1[2] + qf[7] * k1[3]; } }
.LBB0_1628:
	s_add_u32 s12, s2, s54
	s_addc_u32 s13, s3, s55
	v_add_u32_e32 v157, s12, v203
	ds_read_b128 v[56:59], v157
	ds_read_b128 v[60:63], v157 offset:16
	s_waitcnt lgkmcnt(1)
	v_pk_mul_f32 v[56:57], v[56:57], v[54:55]
	v_pk_mul_f32 v[58:59], v[58:59], v[50:51]
	v_add_f32_e32 v45, v56, v57
	v_add_f32_e32 v45, v58, v45
	s_waitcnt lgkmcnt(0)
	v_pk_mul_f32 v[60:61], v[60:61], v[52:53]
	v_add_f32_e32 v45, v59, v45
	v_add_f32_e32 v45, v60, v45
	v_pk_mul_f32 v[62:63], v[62:63], v[48:49]
	v_add_f32_e32 v45, v61, v45
	v_add_f32_e32 v45, v62, v45
	v_add_f32_e32 v45, v63, v45
	v_add_f32_e32 v3, v3, v45
	v_cndmask_b32_e64 v45, 0, 1, s[26:27]
	v_cmp_ne_u32_e64 s[12:13], 1, v45
	s_andn2_b64 vcc, exec, s[26:27]
	s_cbranch_vccnz .LBB0_1514
.LBB0_1629:
	s_add_u32 s14, s2, s46
	s_addc_u32 s15, s3, s47
	v_add_u32_e32 v157, s14, v203
	ds_read_b128 v[56:59], v157
	ds_read_b128 v[60:63], v157 offset:16
	s_waitcnt lgkmcnt(1)
	v_pk_mul_f32 v[56:57], v[56:57], v[54:55]
	v_pk_mul_f32 v[58:59], v[58:59], v[50:51]
	v_add_f32_e32 v45, v56, v57
	v_add_f32_e32 v45, v58, v45
	s_waitcnt lgkmcnt(0)
	v_pk_mul_f32 v[60:61], v[60:61], v[52:53]
	v_add_f32_e32 v45, v59, v45
	v_add_f32_e32 v45, v60, v45
	v_pk_mul_f32 v[62:63], v[62:63], v[48:49]
	v_add_f32_e32 v45, v61, v45
	v_add_f32_e32 v45, v62, v45
	v_add_f32_e32 v45, v63, v45
	v_add_f32_e32 v4, v4, v45
	v_cndmask_b32_e64 v45, 0, 1, s[24:25]
	v_cmp_ne_u32_e64 s[14:15], 1, v45
	s_andn2_b64 vcc, exec, s[24:25]
	s_cbranch_vccnz .LBB0_1515
.LBB0_1630:
	s_add_u32 s20, s2, s90
	s_addc_u32 s21, s3, s91
	v_add_u32_e32 v157, s20, v203
	ds_read_b128 v[56:59], v157
	ds_read_b128 v[60:63], v157 offset:16
	s_waitcnt lgkmcnt(1)
	v_pk_mul_f32 v[56:57], v[56:57], v[54:55]
	v_pk_mul_f32 v[58:59], v[58:59], v[50:51]
	v_add_f32_e32 v45, v56, v57
	v_add_f32_e32 v45, v58, v45
	s_waitcnt lgkmcnt(0)
	v_pk_mul_f32 v[60:61], v[60:61], v[52:53]
	v_add_f32_e32 v45, v59, v45
	v_add_f32_e32 v45, v60, v45
	v_pk_mul_f32 v[62:63], v[62:63], v[48:49]
	v_add_f32_e32 v45, v61, v45
	v_add_f32_e32 v45, v62, v45
	v_add_f32_e32 v45, v63, v45
	v_add_f32_e32 v5, v5, v45
	v_cndmask_b32_e64 v45, 0, 1, s[28:29]
	v_cmp_ne_u32_e64 s[20:21], 1, v45
	s_andn2_b64 vcc, exec, s[28:29]
	s_cbranch_vccz .LBB0_1516
	s_branch .LBB0_1517
.LBB0_1631:
	s_add_u32 s40, s2, s4
	s_addc_u32 s41, s3, s5
	v_add_u32_e32 v157, s40, v203
	ds_read_b128 v[56:59], v157
	ds_read_b128 v[60:63], v157 offset:16
	s_waitcnt lgkmcnt(1)
	v_pk_mul_f32 v[56:57], v[56:57], v[54:55]
	v_pk_mul_f32 v[58:59], v[58:59], v[50:51]
	v_add_f32_e32 v45, v56, v57
	v_add_f32_e32 v45, v58, v45
	s_waitcnt lgkmcnt(0)
	v_pk_mul_f32 v[60:61], v[60:61], v[52:53]
	v_add_f32_e32 v45, v59, v45
	v_add_f32_e32 v45, v60, v45
	v_pk_mul_f32 v[62:63], v[62:63], v[48:49]
	v_add_f32_e32 v45, v61, v45
	v_add_f32_e32 v45, v62, v45
	v_add_f32_e32 v45, v63, v45
	v_add_f32_e32 v1, v1, v45
	s_and_b64 vcc, exec, s[18:19]
	s_cbranch_vccnz .LBB0_1521
.LBB0_1632:
	s_add_u32 s40, s2, s52
	s_addc_u32 s41, s3, s53
	v_add_u32_e32 v157, s40, v203
	ds_read_b128 v[56:59], v157
	ds_read_b128 v[60:63], v157 offset:16
	s_waitcnt lgkmcnt(1)
	v_pk_mul_f32 v[56:57], v[56:57], v[54:55]
	v_pk_mul_f32 v[58:59], v[58:59], v[50:51]
	v_add_f32_e32 v45, v56, v57
	v_add_f32_e32 v45, v58, v45
	s_waitcnt lgkmcnt(0)
	v_pk_mul_f32 v[60:61], v[60:61], v[52:53]
	v_add_f32_e32 v45, v59, v45
	v_add_f32_e32 v45, v60, v45
	v_pk_mul_f32 v[62:63], v[62:63], v[48:49]
	v_add_f32_e32 v45, v61, v45
	v_add_f32_e32 v45, v62, v45
	v_add_f32_e32 v45, v63, v45
	v_add_f32_e32 v2, v2, v45
	s_and_b64 vcc, exec, s[10:11]
	s_cbranch_vccnz .LBB0_1522
.LBB0_1633:
	s_add_u32 s40, s2, s54
	s_addc_u32 s41, s3, s55
	v_add_u32_e32 v157, s40, v203
	ds_read_b128 v[56:59], v157
	ds_read_b128 v[60:63], v157 offset:16
	s_waitcnt lgkmcnt(1)
	v_pk_mul_f32 v[56:57], v[56:57], v[54:55]
	v_pk_mul_f32 v[58:59], v[58:59], v[50:51]
	v_add_f32_e32 v45, v56, v57
	v_add_f32_e32 v45, v58, v45
	s_waitcnt lgkmcnt(0)
	v_pk_mul_f32 v[60:61], v[60:61], v[52:53]
	v_add_f32_e32 v45, v59, v45
	v_add_f32_e32 v45, v60, v45
	v_pk_mul_f32 v[62:63], v[62:63], v[48:49]
	v_add_f32_e32 v45, v61, v45
	v_add_f32_e32 v45, v62, v45
	v_add_f32_e32 v45, v63, v45
	v_add_f32_e32 v3, v3, v45
	s_and_b64 vcc, exec, s[12:13]
	s_cbranch_vccnz .LBB0_1523
.LBB0_1634:
	s_add_u32 s40, s2, s46
	s_addc_u32 s41, s3, s47
	v_add_u32_e32 v157, s40, v203
	ds_read_b128 v[56:59], v157
	ds_read_b128 v[60:63], v157 offset:16
	s_waitcnt lgkmcnt(1)
	v_pk_mul_f32 v[56:57], v[56:57], v[54:55]
	v_pk_mul_f32 v[58:59], v[58:59], v[50:51]
	v_add_f32_e32 v45, v56, v57
	v_add_f32_e32 v45, v58, v45
	s_waitcnt lgkmcnt(0)
	v_pk_mul_f32 v[60:61], v[60:61], v[52:53]
	v_add_f32_e32 v45, v59, v45
	v_add_f32_e32 v45, v60, v45
	v_pk_mul_f32 v[62:63], v[62:63], v[48:49]
	v_add_f32_e32 v45, v61, v45
	v_add_f32_e32 v45, v62, v45
	v_add_f32_e32 v45, v63, v45
	v_add_f32_e32 v4, v4, v45
	s_and_b64 vcc, exec, s[14:15]
	s_cbranch_vccnz .LBB0_1524
.LBB0_1635:
	s_add_u32 s40, s2, s90
	s_addc_u32 s41, s3, s91
	v_add_u32_e32 v157, s40, v203
	ds_read_b128 v[56:59], v157
	ds_read_b128 v[60:63], v157 offset:16
	s_waitcnt lgkmcnt(1)
	v_pk_mul_f32 v[56:57], v[56:57], v[54:55]
	v_pk_mul_f32 v[58:59], v[58:59], v[50:51]
	v_add_f32_e32 v45, v56, v57
	v_add_f32_e32 v45, v58, v45
	s_waitcnt lgkmcnt(0)
	v_pk_mul_f32 v[60:61], v[60:61], v[52:53]
	v_add_f32_e32 v45, v59, v45
	v_add_f32_e32 v45, v60, v45
	v_pk_mul_f32 v[62:63], v[62:63], v[48:49]
	v_add_f32_e32 v45, v61, v45
	v_add_f32_e32 v45, v62, v45
	v_add_f32_e32 v45, v63, v45
	v_add_f32_e32 v5, v5, v45
	s_and_b64 vcc, exec, s[20:21]
	s_cbranch_vccz .LBB0_1525
	s_branch .LBB0_1526

; __device__ __forceinline__ float bflo(unsigned w) { return __uint_as_float(w << 16); }
; __device__ __forceinline__ float bfhi(unsigned w) { return __uint_as_float(w & 0xffff0000u); }
; #define kmean WSP(float, WS_KMEAN)
; __device__ __forceinline__ void attn_item(LAS unsigned char* lds, const bf16_t* z, const float* kmean, bf16_t* cat, int b, int h, int j) {
;     ...
; #pragma unroll
;         for (int c = 0; c < 8; ++c) { const u32x4 w = *(const u32x4*)(qp + c * 8);
;             const float qf[8] = {bflo(w.x), bfhi(w.x), bflo(w.y), bfhi(w.y), bflo(w.z), bfhi(w.z), bflo(w.w), bfhi(w.w)};
; #pragma unroll
;             for (int n = 0; n < 7; ++n) if (n < j) { const float* km = kmean + (size_t)(((b * 16 + h) * 8) + n) * 64 + c * 8;
;                 const f32x4 k0 = *(const f32x4*)km, k1 = *(const f32x4*)(km + 4);
;                 gate[n] += qf[0] * k0[0] + qf[1] * k0[1] + qf[2] * k0[2] + qf[3] * k0[3] + qf[4] * k1[0] + qf[5] * k1[1] + qf[6] * k1[2] + qf[7] * k1[3]; } }
.LBB0_1656:
	s_add_u32 s36, s2, s4
	s_addc_u32 s37, s3, s5
	v_add_u32_e32 v157, s36, v203
	ds_read_b128 v[54:57], v157
	ds_read_b128 v[58:61], v157 offset:16
	s_waitcnt lgkmcnt(1)
	v_pk_mul_f32 v[54:55], v[54:55], v[52:53]
	v_pk_mul_f32 v[56:57], v[56:57], v[48:49]
	v_add_f32_e32 v45, v54, v55
	v_add_f32_e32 v45, v56, v45
	s_waitcnt lgkmcnt(0)
	v_pk_mul_f32 v[58:59], v[58:59], v[50:51]
	v_add_f32_e32 v45, v57, v45
	v_add_f32_e32 v45, v58, v45
	v_pk_mul_f32 v[60:61], v[60:61], v[46:47]
	v_add_f32_e32 v45, v59, v45
	v_add_f32_e32 v45, v60, v45
	v_add_f32_e32 v45, v61, v45
	v_add_f32_e32 v1, v1, v45
	s_and_b64 vcc, exec, s[18:19]
	s_cbranch_vccnz .LBB0_1566
.LBB0_1657:
	s_add_u32 s36, s2, s52
	s_addc_u32 s37, s3, s53
	v_add_u32_e32 v157, s36, v203
	ds_read_b128 v[54:57], v157
	ds_read_b128 v[58:61], v157 offset:16
	s_waitcnt lgkmcnt(1)
	v_pk_mul_f32 v[54:55], v[54:55], v[52:53]
	v_pk_mul_f32 v[56:57], v[56:57], v[48:49]
	v_add_f32_e32 v45, v54, v55
	v_add_f32_e32 v45, v56, v45
	s_waitcnt lgkmcnt(0)
	v_pk_mul_f32 v[58:59], v[58:59], v[50:51]
	v_add_f32_e32 v45, v57, v45
	v_add_f32_e32 v45, v58, v45
	v_pk_mul_f32 v[60:61], v[60:61], v[46:47]
	v_add_f32_e32 v45, v59, v45
	v_add_f32_e32 v45, v60, v45
	v_add_f32_e32 v45, v61, v45
	v_add_f32_e32 v2, v2, v45
	s_and_b64 vcc, exec, s[10:11]
	s_cbranch_vccnz .LBB0_1567
.LBB0_1658:
	s_add_u32 s36, s2, s54
	s_addc_u32 s37, s3, s55
	v_add_u32_e32 v157, s36, v203
	ds_read_b128 v[54:57], v157
	ds_read_b128 v[58:61], v157 offset:16
	s_waitcnt lgkmcnt(1)
	v_pk_mul_f32 v[54:55], v[54:55], v[52:53]
	v_pk_mul_f32 v[56:57], v[56:57], v[48:49]
	v_add_f32_e32 v45, v54, v55
	v_add_f32_e32 v45, v56, v45
	s_waitcnt lgkmcnt(0)
	v_pk_mul_f32 v[58:59], v[58:59], v[50:51]
	v_add_f32_e32 v45, v57, v45
	v_add_f32_e32 v45, v58, v45
	v_pk_mul_f32 v[60:61], v[60:61], v[46:47]
	v_add_f32_e32 v45, v59, v45
	v_add_f32_e32 v45, v60, v45
	v_add_f32_e32 v45, v61, v45
	v_add_f32_e32 v3, v3, v45
	s_and_b64 vcc, exec, s[12:13]
	s_cbranch_vccnz .LBB0_1568
.LBB0_1659:
	s_add_u32 s36, s2, s46
	s_addc_u32 s37, s3, s47
	v_add_u32_e32 v157, s36, v203
	ds_read_b128 v[54:57], v157
	ds_read_b128 v[58:61], v157 offset:16
	s_waitcnt lgkmcnt(1)
	v_pk_mul_f32 v[54:55], v[54:55], v[52:53]
	v_pk_mul_f32 v[56:57], v[56:57], v[48:49]
	v_add_f32_e32 v45, v54, v55
	v_add_f32_e32 v45, v56, v45
	s_waitcnt lgkmcnt(0)
	v_pk_mul_f32 v[58:59], v[58:59], v[50:51]
	v_add_f32_e32 v45, v57, v45
	v_add_f32_e32 v45, v58, v45
	v_pk_mul_f32 v[60:61], v[60:61], v[46:47]
	v_add_f32_e32 v45, v59, v45
	v_add_f32_e32 v45, v60, v45
	v_add_f32_e32 v45, v61, v45
	v_add_f32_e32 v4, v4, v45
	s_and_b64 vcc, exec, s[14:15]
	s_cbranch_vccnz .LBB0_1569
.LBB0_1660:
	s_add_u32 s36, s2, s90
	s_addc_u32 s37, s3, s91
	v_add_u32_e32 v157, s36, v203
	ds_read_b128 v[54:57], v157
	ds_read_b128 v[58:61], v157 offset:16
	s_waitcnt lgkmcnt(1)
	v_pk_mul_f32 v[54:55], v[54:55], v[52:53]
	v_pk_mul_f32 v[56:57], v[56:57], v[48:49]
	v_add_f32_e32 v45, v54, v55
	v_add_f32_e32 v45, v56, v45
	s_waitcnt lgkmcnt(0)
	v_pk_mul_f32 v[58:59], v[58:59], v[50:51]
	v_add_f32_e32 v45, v57, v45
	v_add_f32_e32 v45, v58, v45
	v_pk_mul_f32 v[60:61], v[60:61], v[46:47]
	v_add_f32_e32 v45, v59, v45
	v_add_f32_e32 v45, v60, v45
	v_add_f32_e32 v45, v61, v45
	v_add_f32_e32 v5, v5, v45
	s_and_b64 vcc, exec, s[20:21]
	s_cbranch_vccnz .LBB0_1570
.LBB0_1661:
	s_add_u32 s2, s2, s6
	s_addc_u32 s3, s3, s7
	v_add_u32_e32 v157, s2, v203
	ds_read_b128 v[54:57], v157
	ds_read_b128 v[58:61], v157 offset:16
	s_waitcnt lgkmcnt(1)
	v_pk_mul_f32 v[52:53], v[54:55], v[52:53]
	v_pk_mul_f32 v[48:49], v[56:57], v[48:49]
	v_add_f32_e32 v45, v52, v53
	v_add_f32_e32 v45, v48, v45
	s_waitcnt lgkmcnt(0)
	v_pk_mul_f32 v[50:51], v[58:59], v[50:51]
	v_add_f32_e32 v45, v49, v45
	v_add_f32_e32 v45, v50, v45
	v_pk_mul_f32 v[46:47], v[60:61], v[46:47]
	v_add_f32_e32 v45, v51, v45
	v_add_f32_e32 v45, v46, v45
	v_add_f32_e32 v45, v47, v45
	v_add_f32_e32 v6, v6, v45
	s_and_b64 vcc, exec, s[8:9]
	s_cbranch_vccz .LBB0_1571
